# phase 0: odd workgroups stream x to bf16 first and convert w_in afterwards (the others the other way round)
# speedup vs baseline: 1.0045x; 1.0045x over previous
.LBB0_7:
	s_or_b64 exec, exec, s[4:5]
	s_cmp_lt_i32 s50, 1
	s_cselect_b64 s[0:1], -1, 0
	s_cmp_gt_i32 s51, 0
	s_cselect_b64 s[4:5], -1, 0
	s_and_b64 s[8:9], s[0:1], s[4:5]
	s_andn2_b64 vcc, exec, s[8:9]
	v_lshrrev_b32_e32 v179, 6, v178
	s_cbranch_vccnz .LBB0_356
	v_lshl_add_u32 v34, s2, 3, v179
	s_movk_i32 s99, 0x1b10
	s_cmp_eq_u32 s48, 0x100
	s_cselect_b32 s99, 0x1490, s99
	s_mov_b32 s98, 0
	s_bitcmp1_b32 s2, 0
	s_cbranch_scc0 .Ltr_early_entry
	v_and_b32_e32 v36, 63, v178
	v_lshlrev_b32_e32 v37, 3, v178
	s_lshl_b32 s3, s48, 3
	s_add_u32 s10, s46, 0x2e80000
	s_addc_u32 s11, s47, 0
	s_mov_b32 s98, 2
	s_branch .Lp0_rest

.LBB0_312:
	s_or_b64 exec, exec, s[18:19]
	s_cmp_eq_u32 s98, 1
	s_cbranch_scc1 .Ltr_ret1
	s_cmp_eq_u32 s98, 3
	s_cbranch_scc1 .LBB0_356
.Lp0_rest:
	s_waitcnt vmcnt(0) lgkmcnt(0)
	v_lshl_add_u32 v6, s2, 9, v178
	s_movk_i32 s0, 0x7000
	s_lshl_b32 s6, s48, 9
	v_cmp_gt_i32_e32 vcc, s0, v6
	s_and_saveexec_b64 s[4:5], vcc
	s_cbranch_execz .LBB0_315
	v_ashrrev_i32_e32 v7, 31, v6
	v_lshl_add_u64 v[2:3], v[6:7], 4, s[46:47]
	s_mov_b64 s[0:1], 0x1590000
	v_lshl_add_u64 v[8:9], v[2:3], 0, s[0:1]
	s_ashr_i32 s7, s6, 31
	v_mov_b32_e32 v2, 0
	s_lshl_b64 s[12:13], s[6:7], 4
	s_mov_b64 s[14:15], 0
	v_mov_b32_e32 v3, v2
	v_mov_b32_e32 v4, v2
	v_mov_b32_e32 v5, v2
	s_movk_i32 s0, 0x6fff
	v_mov_b32_e32 v1, v6

.LBB0_355:
	s_or_b64 exec, exec, s[10:11]
	s_cmp_eq_u32 s98, 2
	s_cbranch_scc0 .LBB0_356
	v_lshl_add_u32 v34, s2, 3, v179
	s_mov_b32 s98, 3
	s_branch .Ltr_early_entry
